# v60 + SSM carry: 16 SLOC staging loads per half issued together with counted waits (was load/wait/ds_write x16)
# baseline (speedup 1.0000x reference)
.LBB0_264:
	s_xor_b64 s[56:57], s[58:59], -1
	s_or_b32 s58, s27, s19
	s_ashr_i32 s59, s58, 31
	s_lshl_b64 s[30:31], s[58:59], 9
	s_add_u32 s60, s20, s30
	s_addc_u32 s61, s18, s31
	global_load_dwordx4 v[152:155], v2, s[60:61]
	v_add_u32_e32 v216, 0x2000, v2
	v_add_u32_e32 v217, 0x6000, v2
	v_add_u32_e32 v218, 0xa000, v2
	v_add_u32_e32 v219, 0xe000, v2
	global_load_dwordx4 v[156:159], v216, s[60:61]
	global_load_dwordx4 v[160:163], v37, s[60:61]
	global_load_dwordx4 v[164:167], v217, s[60:61]
	global_load_dwordx4 v[168:171], v38, s[60:61]
	global_load_dwordx4 v[172:175], v218, s[60:61]
	global_load_dwordx4 v[176:179], v39, s[60:61]
	global_load_dwordx4 v[180:183], v219, s[60:61]
	v_add_u32_e32 v220, 0x12000, v2
	v_add_u32_e32 v221, 0x16000, v2
	v_add_u32_e32 v222, 0x1a000, v2
	v_add_u32_e32 v223, 0x1e000, v2
	global_load_dwordx4 v[184:187], v40, s[60:61]
	global_load_dwordx4 v[188:191], v220, s[60:61]
	global_load_dwordx4 v[192:195], v41, s[60:61]
	global_load_dwordx4 v[196:199], v221, s[60:61]
	global_load_dwordx4 v[200:203], v42, s[60:61]
	global_load_dwordx4 v[204:207], v222, s[60:61]
	global_load_dwordx4 v[208:211], v43, s[60:61]
	global_load_dwordx4 v[212:215], v223, s[60:61]
	v_lshl_add_u64 v[20:21], s[60:61], 0, v[2:3]
	v_mov_b32_e32 v22, 0
	s_mov_b32 s27, 0
	s_waitcnt vmcnt(15)
	ds_write_b128 v23, v[152:155]
	s_waitcnt vmcnt(14)
	ds_write_b128 v23, v[156:159] offset:8192
	s_waitcnt vmcnt(13)
	ds_write_b128 v23, v[160:163] offset:16384
	s_waitcnt vmcnt(12)
	ds_write_b128 v23, v[164:167] offset:24576
	s_waitcnt vmcnt(11)
	ds_write_b128 v23, v[168:171] offset:32768
	s_waitcnt vmcnt(10)
	ds_write_b128 v23, v[172:175] offset:40960
	s_waitcnt vmcnt(9)
	ds_write_b128 v23, v[176:179] offset:49152
	s_waitcnt vmcnt(8)
	ds_write_b128 v23, v[180:183] offset:57344
	s_waitcnt vmcnt(7)
	ds_write_b128 v25, v[184:187]
	s_waitcnt vmcnt(6)
	ds_write_b128 v26, v[188:191]
	s_waitcnt vmcnt(5)
	ds_write_b128 v27, v[192:195]
	s_waitcnt vmcnt(4)
	ds_write_b128 v28, v[196:199]
	s_waitcnt vmcnt(3)
	ds_write_b128 v29, v[200:203]
	s_waitcnt vmcnt(2)
	ds_write_b128 v30, v[204:207]
	s_waitcnt vmcnt(1)
	ds_write_b128 v31, v[208:211]
	s_waitcnt vmcnt(0)
	ds_write_b128 v32, v[212:215]
	v_mov_b32_e32 v20, 0
	s_waitcnt lgkmcnt(0)
	s_barrier
